# last layer's down-projection epilogue (EpiResid): residual-stream load pairs regrouped to full 128-B lines as in the other two residual epilogues
# baseline (speedup 1.0000x reference)
;     __device__ __forceinline__ void operator()(const f32x4 (&acc)[2][2][4][2], const pg8::Unit& u, int wr, int wc, int fr, int fq) const {
; #pragma unroll
;         for (int ai = 0; ai < 2; ++ai)
; #pragma unroll
;             for (int m = 0; m < 4; ++m) {
;                 const int R = rowbase + u.pm * 256 + ai * 128 + wr * 64 + m * 16 + fr;
;                 const bool islat = R < TL; const int mrow = islat ? (R >> 13) : 8;
;                 const float* src = islat ? rin_l + (size_t)R * DM : rin_c + (size_t)(R - TL) * DM;
;                 float* dst = islat ? rout_l + (size_t)R * DM : rout_c + (size_t)(R - TL) * DM;
;                 const float* gp = gate + (size_t)mrow * MODW;
; #pragma unroll
;                 for (int bj = 0; bj < 2; ++bj)
; #pragma unroll
;                     for (int n = 0; n < 2; ++n) { const int c = u.pn * 256 + bj * 128 + wc * 32 + 8 * fq + 4 * n;
;                         const f32x4 g4 = *(const f32x4*)(gp + c), x4 = *(const f32x4*)(src + c);
;                         *(f32x4*)(dst + c) = x4 + g4 * acc[ai][bj][m][n]; } }
;     }
.LBB0_1298:
	v_lshl_add_u32 v150, s34, 8, v142
	s_mov_b32 s100, 0xaaaaaaaa
	s_mov_b32 s101, 0xaaaaaaaa
	v_mov_b32_e32 v222, 0x1000
	v_mov_b32_e32 v223, 16
	v_cndmask_b32_e64 v242, v222, v223, s[100:101]
	v_mov_b32_e32 v243, 0
	v_add_u32_e32 v151, s52, v150
	v_add_u32_e32 v146, 0xffff0000, v151
	v_ashrrev_i32_e32 v147, 31, v151
	v_cmp_gt_i32_e32 vcc, s33, v151
	v_min_i32_e32 v141, 0x10000, v151
	v_mov_b32_e32 v148, s55
	v_cndmask_b32_e32 v153, 0, v147, vcc
	v_cndmask_b32_e32 v152, v146, v151, vcc
	v_mov_b32_e32 v146, s56
	v_mov_b32_e32 v147, s45
	v_mov_b32_e32 v149, s44
	v_ashrrev_i32_e32 v141, 13, v141
	v_cndmask_b32_e32 v155, v146, v147, vcc
	v_cndmask_b32_e32 v154, v148, v149, vcc
	v_lshlrev_b64 v[152:153], 12, v[152:153]
	v_lshl_or_b32 v140, s35, 8, v144
	v_lshl_add_u64 v[156:157], v[154:155], 0, v[152:153]
	v_mul_i32_i24_e32 v152, 0x1800, v141
	v_ashrrev_i32_e32 v153, 31, v152
	v_ashrrev_i32_e32 v141, 31, v140
	v_lshl_add_u64 v[152:153], v[152:153], 2, s[20:21]
	v_lshlrev_b64 v[140:141], 2, v[140:141]
	v_lshl_add_u64 v[160:161], v[152:153], 0, v[140:141]
	global_load_dwordx4 v[152:155], v[160:161], off
	v_lshl_add_u64 v[180:181], v[156:157], 0, v[140:141]
	v_lshl_add_u64 v[226:227], v[180:181], 0, v[242:243]
	global_load_dwordx4 v[214:217], v[226:227], off offset:-4096
	global_load_dwordx4 v[218:221], v[226:227], off
	s_mov_b64 s[34:35], -1
	s_waitcnt vmcnt(0)
	v_cndmask_b32_e64 v222, v218, v214, s[100:101]
	v_cndmask_b32_e64 v223, v219, v215, s[100:101]
	v_cndmask_b32_e64 v224, v220, v216, s[100:101]
	v_cndmask_b32_e64 v225, v221, v217, s[100:101]
	v_mov_b32_dpp v238, v222 quad_perm:[1,0,3,2] row_mask:0xf bank_mask:0xf
	v_mov_b32_dpp v239, v223 quad_perm:[1,0,3,2] row_mask:0xf bank_mask:0xf
	v_mov_b32_dpp v240, v224 quad_perm:[1,0,3,2] row_mask:0xf bank_mask:0xf
	v_mov_b32_dpp v241, v225 quad_perm:[1,0,3,2] row_mask:0xf bank_mask:0xf
	v_cndmask_b32_e64 v156, v214, v238, s[100:101]
	v_cndmask_b32_e64 v176, v238, v218, s[100:101]
	v_cndmask_b32_e64 v157, v215, v239, s[100:101]
	v_cndmask_b32_e64 v177, v239, v219, s[100:101]
	v_cndmask_b32_e64 v158, v216, v240, s[100:101]
	v_cndmask_b32_e64 v178, v240, v220, s[100:101]
	v_cndmask_b32_e64 v159, v217, v241, s[100:101]
	v_cndmask_b32_e64 v179, v241, v221, s[100:101]
	v_pk_fma_f32 v[128:129], v[128:129], v[154:155], v[158:159]
	v_pk_fma_f32 v[126:127], v[126:127], v[152:153], v[156:157]
	global_store_dwordx4 v[180:181], v[126:129], off
	global_load_dwordx4 v[126:129], v[160:161], off offset:16
	s_waitcnt vmcnt(0)
	v_pk_fma_f32 v[124:125], v[124:125], v[128:129], v[178:179]
	v_pk_fma_f32 v[122:123], v[122:123], v[126:127], v[176:177]
	global_store_dwordx4 v[180:181], v[122:125], off offset:16
	global_load_dwordx4 v[122:125], v[160:161], off offset:512
	s_nop 0
	v_lshl_add_u64 v[226:227], v[180:181], 0, v[242:243]
	global_load_dwordx4 v[214:217], v[226:227], off offset:-3584
	global_load_dwordx4 v[218:221], v[226:227], off offset:512
	s_waitcnt vmcnt(0)
	v_cndmask_b32_e64 v222, v218, v214, s[100:101]
	v_cndmask_b32_e64 v223, v219, v215, s[100:101]
	v_cndmask_b32_e64 v224, v220, v216, s[100:101]
	v_cndmask_b32_e64 v225, v221, v217, s[100:101]
	v_mov_b32_dpp v238, v222 quad_perm:[1,0,3,2] row_mask:0xf bank_mask:0xf
	v_mov_b32_dpp v239, v223 quad_perm:[1,0,3,2] row_mask:0xf bank_mask:0xf
	v_mov_b32_dpp v240, v224 quad_perm:[1,0,3,2] row_mask:0xf bank_mask:0xf
	v_mov_b32_dpp v241, v225 quad_perm:[1,0,3,2] row_mask:0xf bank_mask:0xf
	v_cndmask_b32_e64 v126, v214, v238, s[100:101]
	v_cndmask_b32_e64 v152, v238, v218, s[100:101]
	v_cndmask_b32_e64 v127, v215, v239, s[100:101]
	v_cndmask_b32_e64 v153, v239, v219, s[100:101]
	v_cndmask_b32_e64 v128, v216, v240, s[100:101]
	v_cndmask_b32_e64 v154, v240, v220, s[100:101]
	v_cndmask_b32_e64 v129, v217, v241, s[100:101]
	v_cndmask_b32_e64 v155, v241, v221, s[100:101]
	v_pk_fma_f32 v[120:121], v[120:121], v[124:125], v[128:129]
	v_pk_fma_f32 v[118:119], v[118:119], v[122:123], v[126:127]
	global_store_dwordx4 v[180:181], v[118:121], off offset:512
	global_load_dwordx4 v[118:121], v[160:161], off offset:528
	v_add_u32_e32 v122, 16, v151
	v_min_i32_e32 v123, 0x10000, v122
	v_add_u32_e32 v124, 0xffff0010, v151
	v_ashrrev_i32_e32 v125, 31, v122
	v_ashrrev_i32_e32 v126, 13, v123
	v_cmp_gt_i32_e32 vcc, s33, v122
	v_mul_i32_i24_e32 v126, 0x1800, v126
	v_ashrrev_i32_e32 v127, 31, v126
	v_cndmask_b32_e32 v123, 0, v125, vcc
	v_cndmask_b32_e32 v122, v124, v122, vcc
	v_cndmask_b32_e32 v125, v146, v147, vcc
	v_cndmask_b32_e32 v124, v148, v149, vcc
	v_lshlrev_b64 v[122:123], 12, v[122:123]
	v_lshl_add_u64 v[122:123], v[124:125], 0, v[122:123]
	v_lshl_add_u64 v[124:125], v[126:127], 2, s[20:21]
	v_lshl_add_u64 v[128:129], v[124:125], 0, v[140:141]
	v_lshl_add_u64 v[126:127], v[122:123], 0, v[140:141]
	s_waitcnt vmcnt(0)
	v_pk_fma_f32 v[108:109], v[108:109], v[120:121], v[154:155]
	v_pk_fma_f32 v[106:107], v[106:107], v[118:119], v[152:153]
	global_store_dwordx4 v[180:181], v[106:109], off offset:528
	global_load_dwordx4 v[106:109], v[128:129], off
	s_nop 0
	v_lshl_add_u64 v[226:227], v[126:127], 0, v[242:243]
	global_load_dwordx4 v[214:217], v[226:227], off offset:-4096
	global_load_dwordx4 v[218:221], v[226:227], off
	s_waitcnt vmcnt(0)
;     __device__ __forceinline__ void operator()(const f32x4 (&acc)[2][2][4][2], const pg8::Unit& u, int wr, int wc, int fr, int fq) const {
;     ...
;             for (int m = 0; m < 4; ++m) {
;                 const int R = rowbase + u.pm * 256 + ai * 128 + wr * 64 + m * 16 + fr;
;                 const bool islat = R < TL; const int mrow = islat ? (R >> 13) : 8;
;                 const float* src = islat ? rin_l + (size_t)R * DM : rin_c + (size_t)(R - TL) * DM;
;                 float* dst = islat ? rout_l + (size_t)R * DM : rout_c + (size_t)(R - TL) * DM;
;                 const float* gp = gate + (size_t)mrow * MODW;
; #pragma unroll
;                 for (int bj = 0; bj < 2; ++bj)
; #pragma unroll
;                     for (int n = 0; n < 2; ++n) { const int c = u.pn * 256 + bj * 128 + wc * 32 + 8 * fq + 4 * n;
;                         const f32x4 g4 = *(const f32x4*)(gp + c), x4 = *(const f32x4*)(src + c);
;                         *(f32x4*)(dst + c) = x4 + g4 * acc[ai][bj][m][n]; } }
	v_cndmask_b32_e64 v222, v218, v214, s[100:101]
	v_cndmask_b32_e64 v223, v219, v215, s[100:101]
	v_cndmask_b32_e64 v224, v220, v216, s[100:101]
	v_cndmask_b32_e64 v225, v221, v217, s[100:101]
	v_mov_b32_dpp v238, v222 quad_perm:[1,0,3,2] row_mask:0xf bank_mask:0xf
	v_mov_b32_dpp v239, v223 quad_perm:[1,0,3,2] row_mask:0xf bank_mask:0xf
	v_mov_b32_dpp v240, v224 quad_perm:[1,0,3,2] row_mask:0xf bank_mask:0xf
	v_mov_b32_dpp v241, v225 quad_perm:[1,0,3,2] row_mask:0xf bank_mask:0xf
	v_cndmask_b32_e64 v118, v214, v238, s[100:101]
	v_cndmask_b32_e64 v122, v238, v218, s[100:101]
	v_cndmask_b32_e64 v119, v215, v239, s[100:101]
	v_cndmask_b32_e64 v123, v239, v219, s[100:101]
	v_cndmask_b32_e64 v120, v216, v240, s[100:101]
	v_cndmask_b32_e64 v124, v240, v220, s[100:101]
	v_cndmask_b32_e64 v121, v217, v241, s[100:101]
	v_cndmask_b32_e64 v125, v241, v221, s[100:101]
	v_pk_fma_f32 v[108:109], v[116:117], v[108:109], v[120:121]
	v_pk_fma_f32 v[106:107], v[114:115], v[106:107], v[118:119]
	global_store_dwordx4 v[126:127], v[106:109], off
	global_load_dwordx4 v[106:109], v[128:129], off offset:16
	s_waitcnt vmcnt(0)
	v_pk_fma_f32 v[108:109], v[112:113], v[108:109], v[124:125]
	v_pk_fma_f32 v[106:107], v[110:111], v[106:107], v[122:123]
	global_store_dwordx4 v[126:127], v[106:109], off offset:16
	global_load_dwordx4 v[106:109], v[128:129], off offset:512
	s_nop 0
	v_lshl_add_u64 v[226:227], v[126:127], 0, v[242:243]
	global_load_dwordx4 v[214:217], v[226:227], off offset:-3584
	global_load_dwordx4 v[218:221], v[226:227], off offset:512
	s_waitcnt vmcnt(0)
	v_cndmask_b32_e64 v222, v218, v214, s[100:101]
	v_cndmask_b32_e64 v223, v219, v215, s[100:101]
	v_cndmask_b32_e64 v224, v220, v216, s[100:101]
	v_cndmask_b32_e64 v225, v221, v217, s[100:101]
	v_mov_b32_dpp v238, v222 quad_perm:[1,0,3,2] row_mask:0xf bank_mask:0xf
	v_mov_b32_dpp v239, v223 quad_perm:[1,0,3,2] row_mask:0xf bank_mask:0xf
	v_mov_b32_dpp v240, v224 quad_perm:[1,0,3,2] row_mask:0xf bank_mask:0xf
	v_mov_b32_dpp v241, v225 quad_perm:[1,0,3,2] row_mask:0xf bank_mask:0xf
	v_cndmask_b32_e64 v110, v214, v238, s[100:101]
	v_cndmask_b32_e64 v114, v238, v218, s[100:101]
	v_cndmask_b32_e64 v111, v215, v239, s[100:101]
	v_cndmask_b32_e64 v115, v239, v219, s[100:101]
	v_cndmask_b32_e64 v112, v216, v240, s[100:101]
	v_cndmask_b32_e64 v116, v240, v220, s[100:101]
	v_cndmask_b32_e64 v113, v217, v241, s[100:101]
	v_cndmask_b32_e64 v117, v241, v221, s[100:101]
	v_pk_fma_f32 v[104:105], v[104:105], v[108:109], v[112:113]
	v_pk_fma_f32 v[102:103], v[102:103], v[106:107], v[110:111]
	global_store_dwordx4 v[126:127], v[102:105], off offset:512
	global_load_dwordx4 v[102:105], v[128:129], off offset:528
	v_add_u32_e32 v106, 32, v151
	v_min_i32_e32 v107, 0x10000, v106
	v_add_u32_e32 v108, 0xffff0020, v151
	v_ashrrev_i32_e32 v109, 31, v106
	v_ashrrev_i32_e32 v110, 13, v107
	v_cmp_gt_i32_e32 vcc, s33, v106
	v_mul_i32_i24_e32 v110, 0x1800, v110
	v_ashrrev_i32_e32 v111, 31, v110
	v_cndmask_b32_e32 v107, 0, v109, vcc
	v_cndmask_b32_e32 v106, v108, v106, vcc
	v_cndmask_b32_e32 v109, v146, v147, vcc
	v_cndmask_b32_e32 v108, v148, v149, vcc
	v_lshlrev_b64 v[106:107], 12, v[106:107]
	v_lshl_add_u64 v[106:107], v[108:109], 0, v[106:107]
	v_lshl_add_u64 v[108:109], v[110:111], 2, s[20:21]
	v_lshl_add_u64 v[112:113], v[108:109], 0, v[140:141]
	v_lshl_add_u64 v[110:111], v[106:107], 0, v[140:141]
	s_waitcnt vmcnt(0)
	v_pk_fma_f32 v[92:93], v[92:93], v[104:105], v[116:117]
	v_pk_fma_f32 v[90:91], v[90:91], v[102:103], v[114:115]
	global_store_dwordx4 v[126:127], v[90:93], off offset:528
	global_load_dwordx4 v[90:93], v[112:113], off
	s_nop 0
	v_lshl_add_u64 v[226:227], v[110:111], 0, v[242:243]
	global_load_dwordx4 v[214:217], v[226:227], off offset:-4096
	global_load_dwordx4 v[218:221], v[226:227], off
	s_waitcnt vmcnt(0)
	v_cndmask_b32_e64 v222, v218, v214, s[100:101]
	v_cndmask_b32_e64 v223, v219, v215, s[100:101]
	v_cndmask_b32_e64 v224, v220, v216, s[100:101]
	v_cndmask_b32_e64 v225, v221, v217, s[100:101]
	v_mov_b32_dpp v238, v222 quad_perm:[1,0,3,2] row_mask:0xf bank_mask:0xf
	v_mov_b32_dpp v239, v223 quad_perm:[1,0,3,2] row_mask:0xf bank_mask:0xf
	v_mov_b32_dpp v240, v224 quad_perm:[1,0,3,2] row_mask:0xf bank_mask:0xf
	v_mov_b32_dpp v241, v225 quad_perm:[1,0,3,2] row_mask:0xf bank_mask:0xf
	v_cndmask_b32_e64 v102, v214, v238, s[100:101]
	v_cndmask_b32_e64 v106, v238, v218, s[100:101]
	v_cndmask_b32_e64 v103, v215, v239, s[100:101]
	v_cndmask_b32_e64 v107, v239, v219, s[100:101]
	v_cndmask_b32_e64 v104, v216, v240, s[100:101]
	v_cndmask_b32_e64 v108, v240, v220, s[100:101]
	v_cndmask_b32_e64 v105, v217, v241, s[100:101]
	v_cndmask_b32_e64 v109, v241, v221, s[100:101]
	v_pk_fma_f32 v[92:93], v[100:101], v[92:93], v[104:105]
	v_pk_fma_f32 v[90:91], v[98:99], v[90:91], v[102:103]
	global_store_dwordx4 v[110:111], v[90:93], off
	global_load_dwordx4 v[90:93], v[112:113], off offset:16
	s_waitcnt vmcnt(0)
	v_pk_fma_f32 v[92:93], v[96:97], v[92:93], v[108:109]
	v_pk_fma_f32 v[90:91], v[94:95], v[90:91], v[106:107]
	global_store_dwordx4 v[110:111], v[90:93], off offset:16
	global_load_dwordx4 v[90:93], v[112:113], off offset:512
	s_nop 0
	v_lshl_add_u64 v[226:227], v[110:111], 0, v[242:243]
	global_load_dwordx4 v[214:217], v[226:227], off offset:-3584
	global_load_dwordx4 v[218:221], v[226:227], off offset:512
	s_waitcnt vmcnt(0)
;     __device__ __forceinline__ void operator()(const f32x4 (&acc)[2][2][4][2], const pg8::Unit& u, int wr, int wc, int fr, int fq) const {
;     ...
;             for (int m = 0; m < 4; ++m) {
;                 const int R = rowbase + u.pm * 256 + ai * 128 + wr * 64 + m * 16 + fr;
;                 const bool islat = R < TL; const int mrow = islat ? (R >> 13) : 8;
;                 const float* src = islat ? rin_l + (size_t)R * DM : rin_c + (size_t)(R - TL) * DM;
;                 float* dst = islat ? rout_l + (size_t)R * DM : rout_c + (size_t)(R - TL) * DM;
;                 const float* gp = gate + (size_t)mrow * MODW;
; #pragma unroll
;                 for (int bj = 0; bj < 2; ++bj)
; #pragma unroll
;                     for (int n = 0; n < 2; ++n) { const int c = u.pn * 256 + bj * 128 + wc * 32 + 8 * fq + 4 * n;
;                         const f32x4 g4 = *(const f32x4*)(gp + c), x4 = *(const f32x4*)(src + c);
;                         *(f32x4*)(dst + c) = x4 + g4 * acc[ai][bj][m][n]; } }
	v_cndmask_b32_e64 v222, v218, v214, s[100:101]
	v_cndmask_b32_e64 v223, v219, v215, s[100:101]
	v_cndmask_b32_e64 v224, v220, v216, s[100:101]
	v_cndmask_b32_e64 v225, v221, v217, s[100:101]
	v_mov_b32_dpp v238, v222 quad_perm:[1,0,3,2] row_mask:0xf bank_mask:0xf
	v_mov_b32_dpp v239, v223 quad_perm:[1,0,3,2] row_mask:0xf bank_mask:0xf
	v_mov_b32_dpp v240, v224 quad_perm:[1,0,3,2] row_mask:0xf bank_mask:0xf
	v_mov_b32_dpp v241, v225 quad_perm:[1,0,3,2] row_mask:0xf bank_mask:0xf
	v_cndmask_b32_e64 v94, v214, v238, s[100:101]
	v_cndmask_b32_e64 v98, v238, v218, s[100:101]
	v_cndmask_b32_e64 v95, v215, v239, s[100:101]
	v_cndmask_b32_e64 v99, v239, v219, s[100:101]
	v_cndmask_b32_e64 v96, v216, v240, s[100:101]
	v_cndmask_b32_e64 v100, v240, v220, s[100:101]
	v_cndmask_b32_e64 v97, v217, v241, s[100:101]
	v_cndmask_b32_e64 v101, v241, v221, s[100:101]
	v_pk_fma_f32 v[88:89], v[88:89], v[92:93], v[96:97]
	v_pk_fma_f32 v[86:87], v[86:87], v[90:91], v[94:95]
	global_store_dwordx4 v[110:111], v[86:89], off offset:512
	global_load_dwordx4 v[86:89], v[112:113], off offset:528
	v_add_u32_e32 v90, 48, v151
	v_min_i32_e32 v91, 0x10000, v90
	v_add_u32_e32 v92, 0xffff0030, v151
	v_ashrrev_i32_e32 v93, 31, v90
	v_ashrrev_i32_e32 v94, 13, v91
	v_cmp_gt_i32_e32 vcc, s33, v90
	v_mul_i32_i24_e32 v94, 0x1800, v94
	v_ashrrev_i32_e32 v95, 31, v94
	v_cndmask_b32_e32 v91, 0, v93, vcc
	v_cndmask_b32_e32 v90, v92, v90, vcc
	v_cndmask_b32_e32 v93, v146, v147, vcc
	v_cndmask_b32_e32 v92, v148, v149, vcc
	v_lshlrev_b64 v[90:91], 12, v[90:91]
	v_lshl_add_u64 v[90:91], v[92:93], 0, v[90:91]
	v_lshl_add_u64 v[92:93], v[94:95], 2, s[20:21]
	v_lshl_add_u64 v[96:97], v[92:93], 0, v[140:141]
	v_lshl_add_u64 v[94:95], v[90:91], 0, v[140:141]
	s_waitcnt vmcnt(0)
	v_pk_fma_f32 v[76:77], v[76:77], v[88:89], v[100:101]
	v_pk_fma_f32 v[74:75], v[74:75], v[86:87], v[98:99]
	global_store_dwordx4 v[110:111], v[74:77], off offset:528
	global_load_dwordx4 v[74:77], v[96:97], off
	s_nop 0
	v_lshl_add_u64 v[226:227], v[94:95], 0, v[242:243]
	global_load_dwordx4 v[214:217], v[226:227], off offset:-4096
	global_load_dwordx4 v[218:221], v[226:227], off
	s_waitcnt vmcnt(0)
	v_cndmask_b32_e64 v222, v218, v214, s[100:101]
	v_cndmask_b32_e64 v223, v219, v215, s[100:101]
	v_cndmask_b32_e64 v224, v220, v216, s[100:101]
	v_cndmask_b32_e64 v225, v221, v217, s[100:101]
	v_mov_b32_dpp v238, v222 quad_perm:[1,0,3,2] row_mask:0xf bank_mask:0xf
	v_mov_b32_dpp v239, v223 quad_perm:[1,0,3,2] row_mask:0xf bank_mask:0xf
	v_mov_b32_dpp v240, v224 quad_perm:[1,0,3,2] row_mask:0xf bank_mask:0xf
	v_mov_b32_dpp v241, v225 quad_perm:[1,0,3,2] row_mask:0xf bank_mask:0xf
	v_cndmask_b32_e64 v86, v214, v238, s[100:101]
	v_cndmask_b32_e64 v90, v238, v218, s[100:101]
	v_cndmask_b32_e64 v87, v215, v239, s[100:101]
	v_cndmask_b32_e64 v91, v239, v219, s[100:101]
	v_cndmask_b32_e64 v88, v216, v240, s[100:101]
	v_cndmask_b32_e64 v92, v240, v220, s[100:101]
	v_cndmask_b32_e64 v89, v217, v241, s[100:101]
	v_cndmask_b32_e64 v93, v241, v221, s[100:101]
	v_pk_fma_f32 v[76:77], v[84:85], v[76:77], v[88:89]
	v_pk_fma_f32 v[74:75], v[82:83], v[74:75], v[86:87]
	global_store_dwordx4 v[94:95], v[74:77], off
	global_load_dwordx4 v[74:77], v[96:97], off offset:16
	s_waitcnt vmcnt(0)
	v_pk_fma_f32 v[76:77], v[80:81], v[76:77], v[92:93]
	v_pk_fma_f32 v[74:75], v[78:79], v[74:75], v[90:91]
	global_store_dwordx4 v[94:95], v[74:77], off offset:16
	global_load_dwordx4 v[74:77], v[96:97], off offset:512
	s_nop 0
	v_lshl_add_u64 v[226:227], v[94:95], 0, v[242:243]
	global_load_dwordx4 v[214:217], v[226:227], off offset:-3584
	global_load_dwordx4 v[218:221], v[226:227], off offset:512
	s_waitcnt vmcnt(0)
	v_cndmask_b32_e64 v222, v218, v214, s[100:101]
	v_cndmask_b32_e64 v223, v219, v215, s[100:101]
	v_cndmask_b32_e64 v224, v220, v216, s[100:101]
	v_cndmask_b32_e64 v225, v221, v217, s[100:101]
	v_mov_b32_dpp v238, v222 quad_perm:[1,0,3,2] row_mask:0xf bank_mask:0xf
	v_mov_b32_dpp v239, v223 quad_perm:[1,0,3,2] row_mask:0xf bank_mask:0xf
	v_mov_b32_dpp v240, v224 quad_perm:[1,0,3,2] row_mask:0xf bank_mask:0xf
	v_mov_b32_dpp v241, v225 quad_perm:[1,0,3,2] row_mask:0xf bank_mask:0xf
	v_cndmask_b32_e64 v78, v214, v238, s[100:101]
	v_cndmask_b32_e64 v82, v238, v218, s[100:101]
	v_cndmask_b32_e64 v79, v215, v239, s[100:101]
	v_cndmask_b32_e64 v83, v239, v219, s[100:101]
	v_cndmask_b32_e64 v80, v216, v240, s[100:101]
	v_cndmask_b32_e64 v84, v240, v220, s[100:101]
	v_cndmask_b32_e64 v81, v217, v241, s[100:101]
	v_cndmask_b32_e64 v85, v241, v221, s[100:101]
	v_pk_fma_f32 v[72:73], v[72:73], v[76:77], v[80:81]
	v_pk_fma_f32 v[70:71], v[70:71], v[74:75], v[78:79]
	global_store_dwordx4 v[94:95], v[70:73], off offset:512
	global_load_dwordx4 v[70:73], v[96:97], off offset:528
	v_add_u32_e32 v74, s59, v150
	v_min_i32_e32 v75, 0x10000, v74
	v_ashrrev_i32_e32 v76, 31, v74
	v_add_u32_e32 v77, 0xffff0000, v74
	v_ashrrev_i32_e32 v78, 13, v75
	v_cmp_gt_i32_e32 vcc, s33, v74
	v_mul_i32_i24_e32 v78, 0x1800, v78
	v_ashrrev_i32_e32 v79, 31, v78
	v_cndmask_b32_e32 v75, 0, v76, vcc
	v_cndmask_b32_e32 v74, v77, v74, vcc
	v_cndmask_b32_e32 v77, v146, v147, vcc
	v_cndmask_b32_e32 v76, v148, v149, vcc
	v_lshlrev_b64 v[74:75], 12, v[74:75]
	v_lshl_add_u64 v[74:75], v[76:77], 0, v[74:75]
	v_lshl_add_u64 v[76:77], v[78:79], 2, s[20:21]
	v_lshl_add_u64 v[80:81], v[76:77], 0, v[140:141]
	v_lshl_add_u64 v[78:79], v[74:75], 0, v[140:141]
	s_waitcnt vmcnt(0)
	v_pk_fma_f32 v[68:69], v[68:69], v[72:73], v[84:85]
	v_pk_fma_f32 v[66:67], v[66:67], v[70:71], v[82:83]
	global_store_dwordx4 v[94:95], v[66:69], off offset:528
	global_load_dwordx4 v[66:69], v[80:81], off
	s_nop 0
	v_lshl_add_u64 v[226:227], v[78:79], 0, v[242:243]
	global_load_dwordx4 v[214:217], v[226:227], off offset:-4096
	global_load_dwordx4 v[218:221], v[226:227], off
	s_waitcnt vmcnt(0)
;     __device__ __forceinline__ void operator()(const f32x4 (&acc)[2][2][4][2], const pg8::Unit& u, int wr, int wc, int fr, int fq) const {
;     ...
;             for (int m = 0; m < 4; ++m) {
;                 const int R = rowbase + u.pm * 256 + ai * 128 + wr * 64 + m * 16 + fr;
;                 const bool islat = R < TL; const int mrow = islat ? (R >> 13) : 8;
;                 const float* src = islat ? rin_l + (size_t)R * DM : rin_c + (size_t)(R - TL) * DM;
;                 float* dst = islat ? rout_l + (size_t)R * DM : rout_c + (size_t)(R - TL) * DM;
;                 const float* gp = gate + (size_t)mrow * MODW;
; #pragma unroll
;                 for (int bj = 0; bj < 2; ++bj)
; #pragma unroll
;                     for (int n = 0; n < 2; ++n) { const int c = u.pn * 256 + bj * 128 + wc * 32 + 8 * fq + 4 * n;
;                         const f32x4 g4 = *(const f32x4*)(gp + c), x4 = *(const f32x4*)(src + c);
;                         *(f32x4*)(dst + c) = x4 + g4 * acc[ai][bj][m][n]; } }
	v_cndmask_b32_e64 v222, v218, v214, s[100:101]
	v_cndmask_b32_e64 v223, v219, v215, s[100:101]
	v_cndmask_b32_e64 v224, v220, v216, s[100:101]
	v_cndmask_b32_e64 v225, v221, v217, s[100:101]
	v_mov_b32_dpp v238, v222 quad_perm:[1,0,3,2] row_mask:0xf bank_mask:0xf
	v_mov_b32_dpp v239, v223 quad_perm:[1,0,3,2] row_mask:0xf bank_mask:0xf
	v_mov_b32_dpp v240, v224 quad_perm:[1,0,3,2] row_mask:0xf bank_mask:0xf
	v_mov_b32_dpp v241, v225 quad_perm:[1,0,3,2] row_mask:0xf bank_mask:0xf
	v_cndmask_b32_e64 v70, v214, v238, s[100:101]
	v_cndmask_b32_e64 v74, v238, v218, s[100:101]
	v_cndmask_b32_e64 v71, v215, v239, s[100:101]
	v_cndmask_b32_e64 v75, v239, v219, s[100:101]
	v_cndmask_b32_e64 v72, v216, v240, s[100:101]
	v_cndmask_b32_e64 v76, v240, v220, s[100:101]
	v_cndmask_b32_e64 v73, v217, v241, s[100:101]
	v_cndmask_b32_e64 v77, v241, v221, s[100:101]
	v_pk_fma_f32 v[64:65], v[64:65], v[68:69], v[72:73]
	v_pk_fma_f32 v[62:63], v[62:63], v[66:67], v[70:71]
	global_store_dwordx4 v[78:79], v[62:65], off
	global_load_dwordx4 v[62:65], v[80:81], off offset:16
	s_waitcnt vmcnt(0)
	v_pk_fma_f32 v[60:61], v[60:61], v[64:65], v[76:77]
	v_pk_fma_f32 v[58:59], v[58:59], v[62:63], v[74:75]
	global_store_dwordx4 v[78:79], v[58:61], off offset:16
	global_load_dwordx4 v[58:61], v[80:81], off offset:512
	s_nop 0
	v_lshl_add_u64 v[226:227], v[78:79], 0, v[242:243]
	global_load_dwordx4 v[214:217], v[226:227], off offset:-3584
	global_load_dwordx4 v[218:221], v[226:227], off offset:512
	s_waitcnt vmcnt(0)
	v_cndmask_b32_e64 v222, v218, v214, s[100:101]
	v_cndmask_b32_e64 v223, v219, v215, s[100:101]
	v_cndmask_b32_e64 v224, v220, v216, s[100:101]
	v_cndmask_b32_e64 v225, v221, v217, s[100:101]
	v_mov_b32_dpp v238, v222 quad_perm:[1,0,3,2] row_mask:0xf bank_mask:0xf
	v_mov_b32_dpp v239, v223 quad_perm:[1,0,3,2] row_mask:0xf bank_mask:0xf
	v_mov_b32_dpp v240, v224 quad_perm:[1,0,3,2] row_mask:0xf bank_mask:0xf
	v_mov_b32_dpp v241, v225 quad_perm:[1,0,3,2] row_mask:0xf bank_mask:0xf
	v_cndmask_b32_e64 v62, v214, v238, s[100:101]
	v_cndmask_b32_e64 v66, v238, v218, s[100:101]
	v_cndmask_b32_e64 v63, v215, v239, s[100:101]
	v_cndmask_b32_e64 v67, v239, v219, s[100:101]
	v_cndmask_b32_e64 v64, v216, v240, s[100:101]
	v_cndmask_b32_e64 v68, v240, v220, s[100:101]
	v_cndmask_b32_e64 v65, v217, v241, s[100:101]
	v_cndmask_b32_e64 v69, v241, v221, s[100:101]
	v_pk_fma_f32 v[56:57], v[56:57], v[60:61], v[64:65]
	v_pk_fma_f32 v[54:55], v[54:55], v[58:59], v[62:63]
	global_store_dwordx4 v[78:79], v[54:57], off offset:512
	global_load_dwordx4 v[54:57], v[80:81], off offset:528
	v_add_u32_e32 v58, s60, v150
	v_min_i32_e32 v59, 0x10000, v58
	v_ashrrev_i32_e32 v60, 31, v58
	v_add_u32_e32 v61, 0xffff0000, v58
	v_ashrrev_i32_e32 v62, 13, v59
	v_cmp_gt_i32_e32 vcc, s33, v58
	v_mul_i32_i24_e32 v62, 0x1800, v62
	v_ashrrev_i32_e32 v63, 31, v62
	v_cndmask_b32_e32 v59, 0, v60, vcc
	v_cndmask_b32_e32 v58, v61, v58, vcc
	v_cndmask_b32_e32 v61, v146, v147, vcc
	v_cndmask_b32_e32 v60, v148, v149, vcc
	v_lshlrev_b64 v[58:59], 12, v[58:59]
	v_lshl_add_u64 v[58:59], v[60:61], 0, v[58:59]
	v_lshl_add_u64 v[60:61], v[62:63], 2, s[20:21]
	v_lshl_add_u64 v[64:65], v[60:61], 0, v[140:141]
	v_lshl_add_u64 v[62:63], v[58:59], 0, v[140:141]
	s_waitcnt vmcnt(0)
	v_pk_fma_f32 v[44:45], v[44:45], v[56:57], v[68:69]
	v_pk_fma_f32 v[42:43], v[42:43], v[54:55], v[66:67]
	global_store_dwordx4 v[78:79], v[42:45], off offset:528
	global_load_dwordx4 v[42:45], v[64:65], off
	s_nop 0
	v_lshl_add_u64 v[226:227], v[62:63], 0, v[242:243]
	global_load_dwordx4 v[214:217], v[226:227], off offset:-4096
	global_load_dwordx4 v[218:221], v[226:227], off
	s_waitcnt vmcnt(0)
	v_cndmask_b32_e64 v222, v218, v214, s[100:101]
	v_cndmask_b32_e64 v223, v219, v215, s[100:101]
	v_cndmask_b32_e64 v224, v220, v216, s[100:101]
	v_cndmask_b32_e64 v225, v221, v217, s[100:101]
	v_mov_b32_dpp v238, v222 quad_perm:[1,0,3,2] row_mask:0xf bank_mask:0xf
	v_mov_b32_dpp v239, v223 quad_perm:[1,0,3,2] row_mask:0xf bank_mask:0xf
	v_mov_b32_dpp v240, v224 quad_perm:[1,0,3,2] row_mask:0xf bank_mask:0xf
	v_mov_b32_dpp v241, v225 quad_perm:[1,0,3,2] row_mask:0xf bank_mask:0xf
	v_cndmask_b32_e64 v54, v214, v238, s[100:101]
	v_cndmask_b32_e64 v58, v238, v218, s[100:101]
	v_cndmask_b32_e64 v55, v215, v239, s[100:101]
	v_cndmask_b32_e64 v59, v239, v219, s[100:101]
	v_cndmask_b32_e64 v56, v216, v240, s[100:101]
	v_cndmask_b32_e64 v60, v240, v220, s[100:101]
	v_cndmask_b32_e64 v57, v217, v241, s[100:101]
	v_cndmask_b32_e64 v61, v241, v221, s[100:101]
	v_pk_fma_f32 v[44:45], v[52:53], v[44:45], v[56:57]
	v_pk_fma_f32 v[42:43], v[50:51], v[42:43], v[54:55]
	global_store_dwordx4 v[62:63], v[42:45], off
	global_load_dwordx4 v[42:45], v[64:65], off offset:16
	s_waitcnt vmcnt(0)
	v_pk_fma_f32 v[44:45], v[48:49], v[44:45], v[60:61]
	v_pk_fma_f32 v[42:43], v[46:47], v[42:43], v[58:59]
	global_store_dwordx4 v[62:63], v[42:45], off offset:16
	global_load_dwordx4 v[42:45], v[64:65], off offset:512
	s_nop 0
	v_lshl_add_u64 v[226:227], v[62:63], 0, v[242:243]
	global_load_dwordx4 v[214:217], v[226:227], off offset:-3584
	global_load_dwordx4 v[218:221], v[226:227], off offset:512
	s_waitcnt vmcnt(0)
;     __device__ __forceinline__ void operator()(const f32x4 (&acc)[2][2][4][2], const pg8::Unit& u, int wr, int wc, int fr, int fq) const {
;     ...
;             for (int m = 0; m < 4; ++m) {
;                 const int R = rowbase + u.pm * 256 + ai * 128 + wr * 64 + m * 16 + fr;
;                 const bool islat = R < TL; const int mrow = islat ? (R >> 13) : 8;
;                 const float* src = islat ? rin_l + (size_t)R * DM : rin_c + (size_t)(R - TL) * DM;
;                 float* dst = islat ? rout_l + (size_t)R * DM : rout_c + (size_t)(R - TL) * DM;
;                 const float* gp = gate + (size_t)mrow * MODW;
; #pragma unroll
;                 for (int bj = 0; bj < 2; ++bj)
; #pragma unroll
;                     for (int n = 0; n < 2; ++n) { const int c = u.pn * 256 + bj * 128 + wc * 32 + 8 * fq + 4 * n;
;                         const f32x4 g4 = *(const f32x4*)(gp + c), x4 = *(const f32x4*)(src + c);
;                         *(f32x4*)(dst + c) = x4 + g4 * acc[ai][bj][m][n]; } }
	v_cndmask_b32_e64 v222, v218, v214, s[100:101]
	v_cndmask_b32_e64 v223, v219, v215, s[100:101]
	v_cndmask_b32_e64 v224, v220, v216, s[100:101]
	v_cndmask_b32_e64 v225, v221, v217, s[100:101]
	v_mov_b32_dpp v238, v222 quad_perm:[1,0,3,2] row_mask:0xf bank_mask:0xf
	v_mov_b32_dpp v239, v223 quad_perm:[1,0,3,2] row_mask:0xf bank_mask:0xf
	v_mov_b32_dpp v240, v224 quad_perm:[1,0,3,2] row_mask:0xf bank_mask:0xf
	v_mov_b32_dpp v241, v225 quad_perm:[1,0,3,2] row_mask:0xf bank_mask:0xf
	v_cndmask_b32_e64 v46, v214, v238, s[100:101]
	v_cndmask_b32_e64 v50, v238, v218, s[100:101]
	v_cndmask_b32_e64 v47, v215, v239, s[100:101]
	v_cndmask_b32_e64 v51, v239, v219, s[100:101]
	v_cndmask_b32_e64 v48, v216, v240, s[100:101]
	v_cndmask_b32_e64 v52, v240, v220, s[100:101]
	v_cndmask_b32_e64 v49, v217, v241, s[100:101]
	v_cndmask_b32_e64 v53, v241, v221, s[100:101]
	v_pk_fma_f32 v[40:41], v[40:41], v[44:45], v[48:49]
	v_pk_fma_f32 v[38:39], v[38:39], v[42:43], v[46:47]
	global_store_dwordx4 v[62:63], v[38:41], off offset:512
	global_load_dwordx4 v[38:41], v[64:65], off offset:528
	v_add_u32_e32 v42, s61, v150
	v_min_i32_e32 v43, 0x10000, v42
	v_ashrrev_i32_e32 v44, 31, v42
	v_add_u32_e32 v45, 0xffff0000, v42
	v_ashrrev_i32_e32 v46, 13, v43
	v_cmp_gt_i32_e32 vcc, s33, v42
	v_mul_i32_i24_e32 v46, 0x1800, v46
	v_ashrrev_i32_e32 v47, 31, v46
	v_cndmask_b32_e32 v43, 0, v44, vcc
	v_cndmask_b32_e32 v42, v45, v42, vcc
	v_cndmask_b32_e32 v45, v146, v147, vcc
	v_cndmask_b32_e32 v44, v148, v149, vcc
	v_lshlrev_b64 v[42:43], 12, v[42:43]
	v_lshl_add_u64 v[42:43], v[44:45], 0, v[42:43]
	v_lshl_add_u64 v[44:45], v[46:47], 2, s[20:21]
	v_lshl_add_u64 v[48:49], v[44:45], 0, v[140:141]
	v_lshl_add_u64 v[46:47], v[42:43], 0, v[140:141]
	s_waitcnt vmcnt(0)
	v_pk_fma_f32 v[28:29], v[28:29], v[40:41], v[52:53]
	v_pk_fma_f32 v[26:27], v[26:27], v[38:39], v[50:51]
	global_store_dwordx4 v[62:63], v[26:29], off offset:528
	global_load_dwordx4 v[26:29], v[48:49], off
	s_nop 0
	v_lshl_add_u64 v[226:227], v[46:47], 0, v[242:243]
	global_load_dwordx4 v[214:217], v[226:227], off offset:-4096
	global_load_dwordx4 v[218:221], v[226:227], off
	s_waitcnt vmcnt(0)
	v_cndmask_b32_e64 v222, v218, v214, s[100:101]
	v_cndmask_b32_e64 v223, v219, v215, s[100:101]
	v_cndmask_b32_e64 v224, v220, v216, s[100:101]
	v_cndmask_b32_e64 v225, v221, v217, s[100:101]
	v_mov_b32_dpp v238, v222 quad_perm:[1,0,3,2] row_mask:0xf bank_mask:0xf
	v_mov_b32_dpp v239, v223 quad_perm:[1,0,3,2] row_mask:0xf bank_mask:0xf
	v_mov_b32_dpp v240, v224 quad_perm:[1,0,3,2] row_mask:0xf bank_mask:0xf
	v_mov_b32_dpp v241, v225 quad_perm:[1,0,3,2] row_mask:0xf bank_mask:0xf
	v_cndmask_b32_e64 v38, v214, v238, s[100:101]
	v_cndmask_b32_e64 v42, v238, v218, s[100:101]
	v_cndmask_b32_e64 v39, v215, v239, s[100:101]
	v_cndmask_b32_e64 v43, v239, v219, s[100:101]
	v_cndmask_b32_e64 v40, v216, v240, s[100:101]
	v_cndmask_b32_e64 v44, v240, v220, s[100:101]
	v_cndmask_b32_e64 v41, v217, v241, s[100:101]
	v_cndmask_b32_e64 v45, v241, v221, s[100:101]
	v_pk_fma_f32 v[28:29], v[36:37], v[28:29], v[40:41]
	v_pk_fma_f32 v[26:27], v[34:35], v[26:27], v[38:39]
	global_store_dwordx4 v[46:47], v[26:29], off
	global_load_dwordx4 v[26:29], v[48:49], off offset:16
	s_waitcnt vmcnt(0)
	v_pk_fma_f32 v[28:29], v[32:33], v[28:29], v[44:45]
	v_pk_fma_f32 v[26:27], v[30:31], v[26:27], v[42:43]
	global_store_dwordx4 v[46:47], v[26:29], off offset:16
	global_load_dwordx4 v[26:29], v[48:49], off offset:512
	s_nop 0
	v_lshl_add_u64 v[226:227], v[46:47], 0, v[242:243]
	global_load_dwordx4 v[214:217], v[226:227], off offset:-3584
	global_load_dwordx4 v[218:221], v[226:227], off offset:512
	s_waitcnt vmcnt(0)
;     __device__ __forceinline__ void operator()(const f32x4 (&acc)[2][2][4][2], const pg8::Unit& u, int wr, int wc, int fr, int fq) const {
;     ...
;             for (int m = 0; m < 4; ++m) {
;                 const int R = rowbase + u.pm * 256 + ai * 128 + wr * 64 + m * 16 + fr;
;                 const bool islat = R < TL; const int mrow = islat ? (R >> 13) : 8;
;                 const float* src = islat ? rin_l + (size_t)R * DM : rin_c + (size_t)(R - TL) * DM;
;                 float* dst = islat ? rout_l + (size_t)R * DM : rout_c + (size_t)(R - TL) * DM;
;                 const float* gp = gate + (size_t)mrow * MODW;
; #pragma unroll
;                 for (int bj = 0; bj < 2; ++bj)
; #pragma unroll
;                     for (int n = 0; n < 2; ++n) { const int c = u.pn * 256 + bj * 128 + wc * 32 + 8 * fq + 4 * n;
;                         const f32x4 g4 = *(const f32x4*)(gp + c), x4 = *(const f32x4*)(src + c);
;                         *(f32x4*)(dst + c) = x4 + g4 * acc[ai][bj][m][n]; } }
	v_cndmask_b32_e64 v222, v218, v214, s[100:101]
	v_cndmask_b32_e64 v223, v219, v215, s[100:101]
	v_cndmask_b32_e64 v224, v220, v216, s[100:101]
	v_cndmask_b32_e64 v225, v221, v217, s[100:101]
	v_mov_b32_dpp v238, v222 quad_perm:[1,0,3,2] row_mask:0xf bank_mask:0xf
	v_mov_b32_dpp v239, v223 quad_perm:[1,0,3,2] row_mask:0xf bank_mask:0xf
	v_mov_b32_dpp v240, v224 quad_perm:[1,0,3,2] row_mask:0xf bank_mask:0xf
	v_mov_b32_dpp v241, v225 quad_perm:[1,0,3,2] row_mask:0xf bank_mask:0xf
	v_cndmask_b32_e64 v30, v214, v238, s[100:101]
	v_cndmask_b32_e64 v34, v238, v218, s[100:101]
	v_cndmask_b32_e64 v31, v215, v239, s[100:101]
	v_cndmask_b32_e64 v35, v239, v219, s[100:101]
	v_cndmask_b32_e64 v32, v216, v240, s[100:101]
	v_cndmask_b32_e64 v36, v240, v220, s[100:101]
	v_cndmask_b32_e64 v33, v217, v241, s[100:101]
	v_cndmask_b32_e64 v37, v241, v221, s[100:101]
	v_pk_fma_f32 v[24:25], v[24:25], v[28:29], v[32:33]
	v_pk_fma_f32 v[22:23], v[22:23], v[26:27], v[30:31]
	global_store_dwordx4 v[46:47], v[22:25], off offset:512
	global_load_dwordx4 v[22:25], v[48:49], off offset:528
	v_add_u32_e32 v26, s62, v150
	v_min_i32_e32 v30, 0x10000, v26
	v_ashrrev_i32_e32 v27, 31, v26
	v_add_u32_e32 v28, 0xffff0000, v26
	v_cmp_gt_i32_e32 vcc, s33, v26
	v_ashrrev_i32_e32 v30, 13, v30
	v_mul_i32_i24_e32 v30, 0x1800, v30
	v_cndmask_b32_e32 v27, 0, v27, vcc
	v_cndmask_b32_e32 v26, v28, v26, vcc
	v_cndmask_b32_e32 v29, v146, v147, vcc
	v_cndmask_b32_e32 v28, v148, v149, vcc
	v_lshlrev_b64 v[26:27], 12, v[26:27]
	v_ashrrev_i32_e32 v31, 31, v30
	v_lshl_add_u64 v[26:27], v[28:29], 0, v[26:27]
	v_lshl_add_u64 v[28:29], v[30:31], 2, s[20:21]
	v_lshl_add_u64 v[32:33], v[28:29], 0, v[140:141]
	v_lshl_add_u64 v[30:31], v[26:27], 0, v[140:141]
	s_and_b64 vcc, exec, s[38:39]
	s_waitcnt vmcnt(0)
	v_pk_fma_f32 v[12:13], v[12:13], v[24:25], v[36:37]
	v_pk_fma_f32 v[10:11], v[10:11], v[22:23], v[34:35]
	global_store_dwordx4 v[46:47], v[10:13], off offset:528
	global_load_dwordx4 v[10:13], v[32:33], off
	s_nop 0
	v_lshl_add_u64 v[226:227], v[30:31], 0, v[242:243]
	global_load_dwordx4 v[214:217], v[226:227], off offset:-4096
	global_load_dwordx4 v[218:221], v[226:227], off
	s_waitcnt vmcnt(0)
	v_cndmask_b32_e64 v222, v218, v214, s[100:101]
	v_cndmask_b32_e64 v223, v219, v215, s[100:101]
	v_cndmask_b32_e64 v224, v220, v216, s[100:101]
	v_cndmask_b32_e64 v225, v221, v217, s[100:101]
	v_mov_b32_dpp v238, v222 quad_perm:[1,0,3,2] row_mask:0xf bank_mask:0xf
	v_mov_b32_dpp v239, v223 quad_perm:[1,0,3,2] row_mask:0xf bank_mask:0xf
	v_mov_b32_dpp v240, v224 quad_perm:[1,0,3,2] row_mask:0xf bank_mask:0xf
	v_mov_b32_dpp v241, v225 quad_perm:[1,0,3,2] row_mask:0xf bank_mask:0xf
	v_cndmask_b32_e64 v22, v214, v238, s[100:101]
	v_cndmask_b32_e64 v26, v238, v218, s[100:101]
	v_cndmask_b32_e64 v23, v215, v239, s[100:101]
	v_cndmask_b32_e64 v27, v239, v219, s[100:101]
	v_cndmask_b32_e64 v24, v216, v240, s[100:101]
	v_cndmask_b32_e64 v28, v240, v220, s[100:101]
	v_cndmask_b32_e64 v25, v217, v241, s[100:101]
	v_cndmask_b32_e64 v29, v241, v221, s[100:101]
	v_pk_fma_f32 v[12:13], v[20:21], v[12:13], v[24:25]
	v_pk_fma_f32 v[10:11], v[18:19], v[10:11], v[22:23]
	global_store_dwordx4 v[30:31], v[10:13], off
	global_load_dwordx4 v[10:13], v[32:33], off offset:16
	s_waitcnt vmcnt(0)
	v_pk_fma_f32 v[12:13], v[16:17], v[12:13], v[28:29]
	v_pk_fma_f32 v[10:11], v[14:15], v[10:11], v[26:27]
	global_store_dwordx4 v[30:31], v[10:13], off offset:16
	global_load_dwordx4 v[10:13], v[32:33], off offset:512
	s_nop 0
	v_lshl_add_u64 v[226:227], v[30:31], 0, v[242:243]
	global_load_dwordx4 v[214:217], v[226:227], off offset:-3584
	global_load_dwordx4 v[218:221], v[226:227], off offset:512
	s_waitcnt vmcnt(0)
	v_cndmask_b32_e64 v222, v218, v214, s[100:101]
	v_cndmask_b32_e64 v223, v219, v215, s[100:101]
	v_cndmask_b32_e64 v224, v220, v216, s[100:101]
	v_cndmask_b32_e64 v225, v221, v217, s[100:101]
	v_mov_b32_dpp v238, v222 quad_perm:[1,0,3,2] row_mask:0xf bank_mask:0xf
	v_mov_b32_dpp v239, v223 quad_perm:[1,0,3,2] row_mask:0xf bank_mask:0xf
	v_mov_b32_dpp v240, v224 quad_perm:[1,0,3,2] row_mask:0xf bank_mask:0xf
	v_mov_b32_dpp v241, v225 quad_perm:[1,0,3,2] row_mask:0xf bank_mask:0xf
	v_cndmask_b32_e64 v14, v214, v238, s[100:101]
	v_cndmask_b32_e64 v18, v238, v218, s[100:101]
	v_cndmask_b32_e64 v15, v215, v239, s[100:101]
	v_cndmask_b32_e64 v19, v239, v219, s[100:101]
	v_cndmask_b32_e64 v16, v216, v240, s[100:101]
	v_cndmask_b32_e64 v20, v240, v220, s[100:101]
	v_cndmask_b32_e64 v17, v217, v241, s[100:101]
	v_cndmask_b32_e64 v21, v241, v221, s[100:101]
	v_pk_fma_f32 v[8:9], v[8:9], v[12:13], v[16:17]
	v_pk_fma_f32 v[6:7], v[6:7], v[10:11], v[14:15]
	global_store_dwordx4 v[30:31], v[6:9], off offset:512
	global_load_dwordx4 v[6:9], v[32:33], off offset:528
	s_waitcnt vmcnt(0)
	v_pk_fma_f32 v[4:5], v[4:5], v[8:9], v[20:21]
	v_pk_fma_f32 v[2:3], v[2:3], v[6:7], v[18:19]
	global_store_dwordx4 v[30:31], v[2:5], off offset:528
	s_cbranch_vccnz .LBB0_1287
	s_andn2_b64 vcc, exec, s[18:19]
	s_cbranch_vccnz .LBB0_1286
	s_barrier
	s_branch .LBB0_1286
